# ssd_pass2: per-head skip weight fetched in the item prologue instead of at the epilogue start (exposed round trip removed)
# speedup vs baseline: 1.0049x; 1.0049x over previous
.Lsa_i:
	v_readlane_b32 s2, v254, 30
	v_readlane_b32 s3, v254, 31
	s_lshl_b32 s9, s34, 2
	s_add_u32 s2, s2, s9
	s_addc_u32 s3, s3, 0
	global_load_dword v160, v157, s[2:3]
	global_load_dwordx4 v[64:67], v[40:41], off
	global_load_dwordx4 v[48:51], v[40:41], off offset:64
	global_load_dwordx4 v[44:47], v[40:41], off offset:128
	global_load_dwordx4 v[88:91], v[40:41], off offset:192
	global_load_dwordx4 v[100:103], v[86:87], off offset:192
	global_load_dwordx4 v[82:85], v[52:53], off
	global_load_dwordx4 v[68:71], v[60:61], off offset:-4096
	global_load_dwordx4 v[116:119], v[42:43], off
	global_load_dwordx4 v[56:59], v[62:63], off offset:64
	s_nop 0
	global_load_dwordx4 v[40:43], v[62:63], off offset:128
	global_load_dwordx4 v[72:75], v[60:61], off
	global_load_dwordx4 v[52:55], v[60:61], off offset:64
	global_load_dwordx4 v[112:115], v[60:61], off offset:128
	global_load_dwordx4 v[94:97], v[60:61], off offset:192
	global_load_dwordx4 v[104:107], v[62:63], off offset:192
	global_load_dwordx4 v[76:79], v[86:87], off
	s_nop 0
	global_load_dwordx4 v[60:63], v[86:87], off offset:64
	global_load_dwordx4 v[108:111], v[86:87], off offset:128
	global_load_dwordx4 v[0:3], v[2:3], off
	s_nop 0
	global_load_dwordx4 v[4:7], v[4:5], off
	s_nop 0
	global_load_dwordx4 v[8:11], v[32:33], off
	s_nop 0
	global_load_dwordx4 v[12:15], v[12:13], off
	s_nop 0
	global_load_dwordx4 v[16:19], v[16:17], off
	s_nop 0
	global_load_dwordx4 v[20:23], v[20:21], off
	s_nop 0
	global_load_dwordx4 v[24:27], v[24:25], off
	s_nop 0
	global_load_dwordx4 v[28:31], v[28:29], off
	s_nop 0
	global_load_dwordx4 v[32:35], v[34:35], off
	s_nop 0
	global_load_dwordx4 v[36:39], v[36:37], off
	s_lshl_b32 s9, s11, 10
	s_add_i32 s21, s9, 16
	s_lshl_b32 s9, s11, 13
	s_movk_i32 s24, 0x110
	s_add_i32 s1, s1, s9
	v_mul_lo_u32 v81, v177, s24
	s_add_i32 s1, s1, s0
	v_and_b32_e32 v86, 63, v176
	v_bfe_u32 v172, v176, 4, 2
	v_add3_u32 v174, 16, v81, v156
	s_add_i32 s13, s21, 0x4400
	s_add_i32 s1, s1, 0x80000
	v_lshlrev_b32_e32 v173, 3, v172
	s_waitcnt vmcnt(10)
	ds_write_b128 v174, v[82:85] offset:33792
	ds_write_b128 v174, v[116:119] offset:42496
	s_add_i32 s8, s18, 1
	v_lshl_add_u32 v81, v86, 2, s13

.LBB0_220:
	s_waitcnt vmcnt(9)
	v_add_u32_e32 v0, s19, v169
	v_ashrrev_i32_e32 v1, 31, v0
	v_readlane_b32 s0, v251, 24
	v_lshlrev_b64 v[108:109], 12, v[0:1]
	v_readlane_b32 s1, v251, 25
	s_ashr_i32 s35, s34, 31
	v_readlane_b32 s40, v254, 20
	v_lshl_add_u64 v[0:1], s[0:1], 0, v[108:109]
	s_lshl_b32 s28, s17, 1
	s_lshl_b64 s[0:1], s[34:35], 2
	v_readlane_b32 s50, v254, 30
	v_lshl_add_u64 v[0:1], v[0:1], 0, s[28:29]
	v_mov_b32_e32 v133, v157
	v_readlane_b32 s51, v254, 31
	s_add_u32 s0, s50, s0
	v_lshl_add_u64 v[0:1], v[0:1], 0, v[132:133]
	s_addc_u32 s1, s51, s1
	global_load_dwordx4 v[28:31], v[0:1], off
	global_load_dwordx4 v[24:27], v[0:1], off offset:128
	global_load_dwordx4 v[20:23], v[0:1], off offset:256
	global_load_dwordx4 v[16:19], v[0:1], off offset:384
	global_load_dwordx4 v[12:15], v[0:1], off offset:512
	global_load_dwordx4 v[8:11], v[0:1], off offset:640
	global_load_dwordx4 v[4:7], v[0:1], off offset:768
	s_nop 0
	global_load_dwordx4 v[0:3], v[0:1], off offset:896
	v_cmp_lt_i32_e32 vcc, v188, v187
	v_mov_b32_e32 v110, v160
	v_readlane_b32 s0, v253, 62
	s_mov_b32 s56, 0x800000
	v_readlane_b32 s52, v254, 32
	v_add3_u32 v112, s0, v173, v137
	ds_read2_b64 v[104:107], v112 offset1:4
	v_add_u32_e32 v113, 0x1000, v112
	v_add_u32_e32 v118, 0x1800, v112
	s_lshl_b32 s0, s20, 2
	s_add_i32 s0, s0, 16
	s_waitcnt vmcnt(10) lgkmcnt(0)
	v_lshlrev_b32_e32 v32, 16, v104
	v_readlane_b32 s53, v254, 33
	v_readlane_b32 s8, v251, 51
	v_readlane_b32 s9, v251, 52
	v_readlane_b32 s72, v254, 41
	v_readlane_b32 s54, v254, 34
	v_readlane_b32 s55, v254, 35
	v_readlane_b32 s70, v254, 39
	v_readlane_b32 s73, v254, 42
	v_readlane_b32 s74, v254, 44
	v_readlane_b32 s76, v254, 46
	v_readlane_b32 s78, v254, 48
	v_readlane_b32 s82, v254, 52
	v_readlane_b32 s60, v254, 54
	v_readlane_b32 s62, v254, 56
	v_readlane_b32 s64, v254, 58
	v_readlane_b32 s66, v254, 60
	s_movk_i32 s68, 0x2040
	v_readlane_b32 s57, v254, 36
	v_readlane_b32 s58, v254, 37
	v_readlane_b32 s59, v254, 38
	v_readlane_b32 s71, v254, 40
	v_readlane_b32 s69, v254, 43
	v_readlane_b32 s75, v254, 45
	v_readlane_b32 s77, v254, 47
	v_readlane_b32 s79, v254, 49
	v_readlane_b32 s80, v254, 50
	v_readlane_b32 s81, v254, 51
	v_readlane_b32 s83, v254, 53
	v_readlane_b32 s61, v254, 55
	v_readlane_b32 s63, v254, 57
	v_readlane_b32 s65, v254, 59
	v_readlane_b32 s67, v254, 61
	s_movk_i32 s73, 0xf5
	s_movk_i32 s55, 0xfff
	s_mov_b32 s54, 0xf0c0
	v_readlane_b32 s41, v254, 21
	v_readlane_b32 s42, v254, 22
	v_readlane_b32 s43, v254, 23
	v_readlane_b32 s44, v254, 24
	v_readlane_b32 s45, v254, 25
	v_readlane_b32 s46, v254, 26
	v_readlane_b32 s47, v254, 27
	v_readlane_b32 s48, v254, 28
	v_readlane_b32 s49, v254, 29
	v_fma_f32 v111, v110, v32, v40
	v_and_b32_e32 v32, 0xffff0000, v104
	v_fma_f32 v104, v110, v32, v41
	v_lshlrev_b32_e32 v32, 16, v105
	v_fma_f32 v42, v110, v32, v42
	v_and_b32_e32 v32, 0xffff0000, v105
	v_add_u32_e32 v105, 0x800, v112
	ds_read2_b64 v[34:37], v105 offset0:32 offset1:36
	ds_read2_b64 v[38:41], v113 offset0:64 offset1:68
	v_fmac_f32_e32 v43, v110, v32
	ds_read2_b64 v[114:117], v105 offset0:40 offset1:44
	s_waitcnt lgkmcnt(2)
	v_lshlrev_b32_e32 v32, 16, v34
	v_fma_f32 v48, v110, v32, v48
	v_and_b32_e32 v32, 0xffff0000, v34
	v_fma_f32 v49, v110, v32, v49
	v_lshlrev_b32_e32 v32, 16, v35
	v_fma_f32 v50, v110, v32, v50
	v_and_b32_e32 v32, 0xffff0000, v35
	v_fmac_f32_e32 v51, v110, v32
	s_waitcnt lgkmcnt(1)
	v_lshlrev_b32_e32 v32, 16, v38
	v_fma_f32 v44, v110, v32, v44
	v_and_b32_e32 v32, 0xffff0000, v38
	v_fma_f32 v38, v110, v32, v45
	v_lshlrev_b32_e32 v32, 16, v39
	v_fma_f32 v45, v110, v32, v46
	v_and_b32_e32 v32, 0xffff0000, v39
	v_fmac_f32_e32 v47, v110, v32
	ds_read2_b64 v[32:35], v118 offset0:96 offset1:100
	ds_read2_b64 v[118:121], v118 offset0:104 offset1:108
	s_waitcnt lgkmcnt(1)
	v_lshlrev_b32_e32 v46, 16, v33
	v_fma_f32 v46, v110, v46, v54
	v_and_b32_e32 v33, 0xffff0000, v33
	v_and_b32_e32 v54, 0xffff0000, v107
	v_lshlrev_b32_e32 v39, 16, v32
	v_fmac_f32_e32 v55, v110, v33
	v_lshlrev_b32_e32 v33, 16, v106
	v_fmac_f32_e32 v59, v110, v54
	v_lshlrev_b32_e32 v54, 16, v36
	v_and_b32_e32 v36, 0xffff0000, v36
	v_fma_f32 v39, v110, v39, v52
	v_fma_f32 v33, v110, v33, v56
	v_and_b32_e32 v52, 0xffff0000, v106
	v_fma_f32 v56, v110, v36, v61
	v_lshlrev_b32_e32 v36, 16, v37
	v_and_b32_e32 v32, 0xffff0000, v32
	v_fma_f32 v52, v110, v52, v57
	v_fma_f32 v57, v110, v36, v62
	v_and_b32_e32 v36, 0xffff0000, v37
	v_fma_f32 v32, v110, v32, v53
	v_lshlrev_b32_e32 v53, 16, v107
	v_fmac_f32_e32 v63, v110, v36
	v_lshlrev_b32_e32 v36, 16, v40
	v_fma_f32 v53, v110, v53, v58
	v_fma_f32 v58, v110, v36, v64
	v_and_b32_e32 v36, 0xffff0000, v40
	v_fma_f32 v40, v110, v36, v65
	v_lshlrev_b32_e32 v36, 16, v41
	v_fma_f32 v54, v110, v54, v60
	v_fma_f32 v60, v110, v36, v66
	v_and_b32_e32 v36, 0xffff0000, v41
	v_fmac_f32_e32 v67, v110, v36
	v_lshlrev_b32_e32 v36, 16, v34
	v_and_b32_e32 v34, 0xffff0000, v34
	v_fma_f32 v61, v110, v34, v81
	v_lshlrev_b32_e32 v34, 16, v35
	v_fma_f32 v62, v110, v34, v82
	v_and_b32_e32 v34, 0xffff0000, v35
	v_fma_f32 v41, v110, v36, v80
	v_fmac_f32_e32 v83, v110, v34
	ds_read2_b64 v[34:37], v112 offset0:8 offset1:12
	v_and_b32_e32 v66, 0xffff0000, v114
	v_fma_f32 v66, v110, v66, v73
	v_and_b32_e32 v73, 0xffff0000, v115
	v_and_b32_e32 v80, 0xffff0000, v116
	s_waitcnt lgkmcnt(0)
	v_lshlrev_b32_e32 v65, 16, v35
	v_fma_f32 v65, v110, v65, v78
	v_lshlrev_b32_e32 v78, 16, v37
	v_fma_f32 v78, v110, v78, v90
	v_and_b32_e32 v37, 0xffff0000, v37
	v_and_b32_e32 v90, 0xffff0000, v121
	v_and_b32_e32 v35, 0xffff0000, v35
	v_fmac_f32_e32 v91, v110, v37
	v_lshlrev_b32_e32 v37, 16, v116
	v_fmac_f32_e32 v103, v110, v90
	v_lshl_add_u32 v90, v171, 2, s0
	s_movk_i32 s0, 0x2040
	v_fmac_f32_e32 v79, v110, v35
	v_lshlrev_b32_e32 v35, 16, v114
	v_fma_f32 v37, v110, v37, v92
	v_mad_u32_u24 v92, v172, s0, v90
	v_fma_f32 v35, v110, v35, v72
	v_lshlrev_b32_e32 v72, 16, v115
	ds_read2_b64 v[112:115], v113 offset0:72 offset1:76
	s_waitcnt lgkmcnt(0)
	s_barrier
	ds_write2_b32 v92, v111, v48 offset1:16
	v_add_u32_e32 v48, 0x800, v92
	ds_write2_b32 v48, v104, v49 offset0:4 offset1:20
	v_add_u32_e32 v49, 0x1000, v92
	ds_write2_b32 v49, v42, v50 offset0:8 offset1:24
	v_add_u32_e32 v42, 0x1800, v92
	ds_write2_b32 v42, v43, v51 offset0:12 offset1:28
	ds_write2_b32 v92, v44, v39 offset0:32 offset1:48
	ds_write2_b32 v48, v38, v32 offset0:36 offset1:52
	ds_write2_b32 v49, v45, v46 offset0:40 offset1:56
	ds_write2_b32 v42, v47, v55 offset0:44 offset1:60
	v_add_u32_e32 v32, 0x8000, v92
	ds_write2_b32 v32, v33, v54 offset0:64 offset1:80
	v_add_u32_e32 v33, 0x8800, v92
	v_add_u32_e32 v38, 0x9000, v92
	v_add_u32_e32 v39, 0x9800, v92
	ds_write2_b32 v33, v52, v56 offset0:68 offset1:84
	ds_write2_b32 v38, v53, v57 offset0:72 offset1:88
	ds_write2_b32 v39, v59, v63 offset0:76 offset1:92
	ds_write2_b32 v32, v58, v41 offset0:96 offset1:112
	ds_write2_b32 v33, v40, v61 offset0:100 offset1:116
	ds_write2_b32 v38, v60, v62 offset0:104 offset1:120
	ds_write2_b32 v39, v67, v83 offset0:108 offset1:124
	v_mov_b32_e32 v32, 0x10200
	v_lshlrev_b32_e32 v64, 16, v34
	v_mad_u32_u24 v32, v172, s0, v32
	v_fma_f32 v64, v110, v64, v76
	v_add_u32_e32 v33, v90, v32
	ds_write_b32 v33, v64
	v_mov_b32_e32 v33, 0x10a10
	v_and_b32_e32 v34, 0xffff0000, v34
	v_mad_u32_u24 v33, v172, s0, v33
	v_fma_f32 v34, v110, v34, v77
	v_add_u32_e32 v38, v90, v33
	ds_write_b32 v38, v34
	v_mov_b32_e32 v34, 0x11220
	v_mad_u32_u24 v34, v172, s0, v34
	v_add_u32_e32 v38, v90, v34
	ds_write_b32 v38, v65
	v_mov_b32_e32 v38, 0x11a30
	v_mad_u32_u24 v38, v172, s0, v38
	v_fmac_f32_e32 v75, v110, v73
	v_lshlrev_b32_e32 v73, 16, v112
	v_fma_f32 v80, v110, v80, v93
	v_add_u32_e32 v93, 64, v90
	v_add_u32_e32 v39, v90, v38
	v_fma_f32 v68, v110, v73, v68
	v_and_b32_e32 v73, 0xffff0000, v112
	ds_write_b32 v39, v79
	v_add_u32_e32 v39, v93, v32
	v_fma_f32 v69, v110, v73, v69
	v_lshlrev_b32_e32 v73, 16, v113
	ds_write_b32 v39, v35
	v_add_u32_e32 v35, v93, v33
	v_fma_f32 v72, v110, v72, v74
	v_fma_f32 v70, v110, v73, v70
	v_and_b32_e32 v73, 0xffff0000, v113
	ds_write_b32 v35, v66
	v_add_u32_e32 v35, v93, v34
	v_fmac_f32_e32 v71, v110, v73
	v_lshlrev_b32_e32 v73, 16, v118
	v_add_u32_e32 v43, 0x80, v90
	v_add_u32_e32 v50, 0xc0, v90
	ds_write_b32 v35, v72
	v_add_u32_e32 v35, v93, v38
	v_fma_f32 v73, v110, v73, v84
	v_and_b32_e32 v74, 0xffff0000, v118
	ds_write_b32 v35, v75
	v_add_u32_e32 v35, v43, v32
	v_add_u32_e32 v32, v50, v32
	v_fma_f32 v74, v110, v74, v85
	v_lshlrev_b32_e32 v76, 16, v119
	ds_write_b32 v32, v73
	v_add_u32_e32 v32, v50, v33
	v_fma_f32 v76, v110, v76, v86
	v_and_b32_e32 v77, 0xffff0000, v119
	ds_write_b32 v32, v74
	v_add_u32_e32 v32, v50, v34
	v_fmac_f32_e32 v87, v110, v77
	ds_write_b32 v32, v76
	v_add_u32_e32 v32, v50, v38
	ds_write_b32 v32, v87
	v_mov_b32_e32 v32, 0x18300
	v_lshlrev_b32_e32 v77, 16, v36
	v_mad_u32_u24 v32, v172, s0, v32
	v_fma_f32 v77, v110, v77, v88
	ds_write_b32 v35, v68
	v_add_u32_e32 v35, v43, v33
	v_add_u32_e32 v33, v90, v32
	ds_write_b32 v33, v77
	v_mov_b32_e32 v33, 0x18b10
	v_and_b32_e32 v36, 0xffff0000, v36
	v_mad_u32_u24 v33, v172, s0, v33
	v_fma_f32 v36, v110, v36, v89
	ds_write_b32 v35, v69
	v_add_u32_e32 v35, v43, v34
	v_add_u32_e32 v34, v90, v33
	ds_write_b32 v34, v36
	v_mov_b32_e32 v34, 0x19320
	ds_write_b32 v35, v70
	v_add_u32_e32 v35, v43, v38
	v_mad_u32_u24 v34, v172, s0, v34
	ds_write_b32 v35, v71
	v_add_u32_e32 v35, v90, v34
	ds_write_b32 v35, v78
	v_mad_u32_u24 v35, v172, s0, v198
	v_add_u32_e32 v36, v90, v35
	ds_write_b32 v36, v91
	v_add_u32_e32 v36, v93, v32
	v_lshlrev_b32_e32 v81, 16, v117
	ds_write_b32 v36, v37
	v_add_u32_e32 v36, v93, v33
	v_fma_f32 v81, v110, v81, v94
	v_and_b32_e32 v82, 0xffff0000, v117
	v_and_b32_e32 v86, 0xffff0000, v115
	ds_write_b32 v36, v80
	v_add_u32_e32 v36, v93, v34
	v_fmac_f32_e32 v95, v110, v82
	v_fmac_f32_e32 v99, v110, v86
	v_lshlrev_b32_e32 v86, 16, v120
	ds_write_b32 v36, v81
	v_add_u32_e32 v36, v93, v35
	v_fma_f32 v86, v110, v86, v100
	v_and_b32_e32 v88, 0xffff0000, v120
	ds_write_b32 v36, v95
	v_add_u32_e32 v36, v43, v32
	v_add_u32_e32 v32, v50, v32
	v_lshlrev_b32_e32 v82, 16, v114
	v_fma_f32 v88, v110, v88, v101
	v_lshlrev_b32_e32 v89, 16, v121
	ds_write_b32 v32, v86
	v_add_u32_e32 v32, v50, v33
	v_fma_f32 v82, v110, v82, v96
	v_and_b32_e32 v84, 0xffff0000, v114
	v_fma_f32 v89, v110, v89, v102
	ds_write_b32 v32, v88
	v_add_u32_e32 v32, v50, v34
	v_fma_f32 v84, v110, v84, v97
	v_lshlrev_b32_e32 v85, 16, v115
	ds_write_b32 v36, v82
	v_add_u32_e32 v36, v43, v33
	ds_write_b32 v32, v89
	v_add_u32_e32 v32, v50, v35
	s_movk_i32 s0, 0x810
	v_fma_f32 v85, v110, v85, v98
	ds_write_b32 v36, v84
	v_add_u32_e32 v36, v43, v34
	ds_write_b32 v32, v103
	v_mul_lo_u32 v33, v169, s0
	v_lshlrev_b32_e32 v32, 2, v166
	ds_write_b32 v36, v85
	v_add_u32_e32 v36, v43, v35
	v_add3_u32 v76, 16, v33, v32
	ds_write_b32 v36, v99
	s_waitcnt lgkmcnt(0)
	s_barrier
	ds_read_b128 v[34:37], v76
	ds_read_b128 v[38:41], v76 offset:16
	s_waitcnt vmcnt(0)
	s_lshl_b32 s2, s17, 2
	s_add_u32 s2, s52, s2
	s_addc_u32 s3, s53, 0
	global_load_dwordx4 v[204:207], v32, s[2:3] offset:16
	global_load_dwordx4 v[208:211], v32, s[2:3]
	global_load_dwordx4 v[212:215], v32, s[2:3] offset:272
	global_load_dwordx4 v[216:219], v32, s[2:3] offset:256
	global_load_dwordx4 v[220:223], v32, s[2:3] offset:528
	global_load_dwordx4 v[224:227], v32, s[2:3] offset:512
	global_load_dwordx4 v[228:231], v32, s[2:3] offset:784
	global_load_dwordx4 v[232:235], v32, s[2:3] offset:768
	global_load_dwordx4 v[236:239], v32, s[2:3] offset:1040
	global_load_dwordx4 v[240:243], v32, s[2:3] offset:1024
	global_load_dwordx4 v[146:149], v32, s[2:3] offset:1296
	global_load_dwordx4 v[150:153], v32, s[2:3] offset:1280
	global_load_dwordx4 v[168:171], v32, s[2:3] offset:1552
	global_load_dwordx4 v[172:175], v32, s[2:3] offset:1536
	global_load_dwordx4 v[176:179], v32, s[2:3] offset:1808
	v_lshlrev_b32_e32 v33, 16, v28
	v_and_b32_e32 v28, 0xffff0000, v28
	v_lshlrev_b32_e32 v42, 16, v29
	s_waitcnt lgkmcnt(1)
	v_mul_f32_e32 v72, v35, v28
	v_mul_f32_e32 v73, v34, v33
	v_mul_f32_e32 v77, v72, v72
	v_and_b32_e32 v29, 0xffff0000, v29
	v_mul_f32_e32 v71, v36, v42
	v_fmac_f32_e32 v77, v73, v73
	v_lshlrev_b32_e32 v43, 16, v30
	v_and_b32_e32 v30, 0xffff0000, v30
	v_lshlrev_b32_e32 v44, 16, v31
	v_and_b32_e32 v31, 0xffff0000, v31
	v_mul_f32_e32 v70, v37, v29
	v_fmac_f32_e32 v77, v71, v71
	s_waitcnt lgkmcnt(0)
	v_mul_f32_e32 v69, v38, v43
	v_mul_f32_e32 v68, v39, v30
	v_mul_f32_e32 v65, v41, v31
	v_fmac_f32_e32 v77, v70, v70
	ds_read_b128 v[28:31], v76 offset:256
	ds_read_b128 v[34:37], v76 offset:272
	v_fmac_f32_e32 v77, v69, v69
	v_mul_f32_e32 v67, v40, v44
	v_fmac_f32_e32 v77, v68, v68
	v_fmac_f32_e32 v77, v67, v67
	v_lshlrev_b32_e32 v33, 16, v24
	v_fmac_f32_e32 v77, v65, v65
	v_and_b32_e32 v24, 0xffff0000, v24
	s_waitcnt lgkmcnt(1)
	v_mul_f32_e32 v66, v28, v33
	v_lshlrev_b32_e32 v38, 16, v25
	v_mul_f32_e32 v63, v29, v24
	v_fmac_f32_e32 v77, v66, v66
	v_and_b32_e32 v25, 0xffff0000, v25
	v_mul_f32_e32 v60, v30, v38
	v_fmac_f32_e32 v77, v63, v63
	v_lshlrev_b32_e32 v39, 16, v26
	v_and_b32_e32 v26, 0xffff0000, v26
	v_lshlrev_b32_e32 v40, 16, v27
	v_and_b32_e32 v27, 0xffff0000, v27
	v_mul_f32_e32 v56, v31, v25
	v_fmac_f32_e32 v77, v60, v60
	s_waitcnt lgkmcnt(0)
	v_mul_f32_e32 v51, v34, v39
	v_mul_f32_e32 v45, v35, v26
	v_mul_f32_e32 v35, v37, v27
	v_fmac_f32_e32 v77, v56, v56
	ds_read_b128 v[24:27], v76 offset:512
	ds_read_b128 v[28:31], v76 offset:528
	v_fmac_f32_e32 v77, v51, v51
	v_mul_f32_e32 v40, v36, v40
	v_fmac_f32_e32 v77, v45, v45
	v_fmac_f32_e32 v77, v40, v40
	v_lshlrev_b32_e32 v33, 16, v20
	v_fmac_f32_e32 v77, v35, v35
	v_and_b32_e32 v20, 0xffff0000, v20
	s_waitcnt lgkmcnt(1)
	v_mul_f32_e32 v64, v24, v33
	v_lshlrev_b32_e32 v34, 16, v21
	v_mul_f32_e32 v61, v25, v20
	v_fmac_f32_e32 v77, v64, v64
	v_and_b32_e32 v21, 0xffff0000, v21
	v_mul_f32_e32 v57, v26, v34
	v_fmac_f32_e32 v77, v61, v61
	v_lshlrev_b32_e32 v36, 16, v22
	v_and_b32_e32 v22, 0xffff0000, v22
	v_lshlrev_b32_e32 v37, 16, v23
	v_and_b32_e32 v23, 0xffff0000, v23
	v_mul_f32_e32 v52, v27, v21
	v_fmac_f32_e32 v77, v57, v57
	s_waitcnt lgkmcnt(0)
	v_mul_f32_e32 v46, v28, v36
	v_mul_f32_e32 v41, v29, v22
	v_mul_f32_e32 v36, v30, v37
	v_mul_f32_e32 v30, v31, v23
	v_fmac_f32_e32 v77, v52, v52
	ds_read_b128 v[20:23], v76 offset:768
	ds_read_b128 v[24:27], v76 offset:784
	v_fmac_f32_e32 v77, v46, v46
	v_fmac_f32_e32 v77, v41, v41
	v_fmac_f32_e32 v77, v36, v36
	v_lshlrev_b32_e32 v28, 16, v16
	v_fmac_f32_e32 v77, v30, v30
	v_and_b32_e32 v16, 0xffff0000, v16
	s_waitcnt lgkmcnt(1)
	v_mul_f32_e32 v62, v20, v28
	v_lshlrev_b32_e32 v29, 16, v17
	v_mul_f32_e32 v58, v21, v16
	v_fmac_f32_e32 v77, v62, v62
	v_and_b32_e32 v17, 0xffff0000, v17
	v_mul_f32_e32 v53, v22, v29
	v_fmac_f32_e32 v77, v58, v58
	v_lshlrev_b32_e32 v31, 16, v18
	v_and_b32_e32 v18, 0xffff0000, v18
	v_lshlrev_b32_e32 v33, 16, v19
	v_and_b32_e32 v19, 0xffff0000, v19
	v_mul_f32_e32 v47, v23, v17
	v_fmac_f32_e32 v77, v53, v53
	s_waitcnt lgkmcnt(0)
	v_mul_f32_e32 v42, v24, v31
	v_mul_f32_e32 v37, v25, v18
	v_mul_f32_e32 v27, v27, v19
	v_fmac_f32_e32 v77, v47, v47
	ds_read_b128 v[16:19], v76 offset:1024
	ds_read_b128 v[20:23], v76 offset:1040
	v_fmac_f32_e32 v77, v42, v42
	v_mul_f32_e32 v31, v26, v33
	v_fmac_f32_e32 v77, v37, v37
	v_fmac_f32_e32 v77, v31, v31
	v_lshlrev_b32_e32 v24, 16, v12
	v_fmac_f32_e32 v77, v27, v27
	v_and_b32_e32 v12, 0xffff0000, v12
	s_waitcnt lgkmcnt(1)
	v_mul_f32_e32 v59, v16, v24
	v_lshlrev_b32_e32 v25, 16, v13
	v_mul_f32_e32 v54, v17, v12
	v_fmac_f32_e32 v77, v59, v59
	v_and_b32_e32 v13, 0xffff0000, v13
	v_mul_f32_e32 v48, v18, v25
	v_fmac_f32_e32 v77, v54, v54
	v_lshlrev_b32_e32 v26, 16, v14
	v_and_b32_e32 v14, 0xffff0000, v14
	v_lshlrev_b32_e32 v28, 16, v15
	v_and_b32_e32 v15, 0xffff0000, v15
	v_mul_f32_e32 v43, v19, v13
	v_fmac_f32_e32 v77, v48, v48
	s_waitcnt lgkmcnt(0)
	v_mul_f32_e32 v38, v20, v26
	v_mul_f32_e32 v33, v21, v14
	v_mul_f32_e32 v24, v23, v15
	v_fmac_f32_e32 v77, v43, v43
	ds_read_b128 v[12:15], v76 offset:1280
	ds_read_b128 v[16:19], v76 offset:1296
	v_fmac_f32_e32 v77, v38, v38
	v_mul_f32_e32 v28, v22, v28
	v_fmac_f32_e32 v77, v33, v33
	v_fmac_f32_e32 v77, v28, v28
	v_lshlrev_b32_e32 v20, 16, v8
	v_fmac_f32_e32 v77, v24, v24
	v_and_b32_e32 v8, 0xffff0000, v8
	s_waitcnt lgkmcnt(1)
	v_mul_f32_e32 v55, v12, v20
	v_lshlrev_b32_e32 v21, 16, v9
	v_mul_f32_e32 v49, v13, v8
	v_fmac_f32_e32 v77, v55, v55
	v_and_b32_e32 v9, 0xffff0000, v9
	v_mul_f32_e32 v44, v14, v21
	v_fmac_f32_e32 v77, v49, v49
	v_lshlrev_b32_e32 v22, 16, v10
	v_and_b32_e32 v10, 0xffff0000, v10
	v_lshlrev_b32_e32 v23, 16, v11
	v_and_b32_e32 v11, 0xffff0000, v11
	v_mul_f32_e32 v39, v15, v9
	v_fmac_f32_e32 v77, v44, v44
	s_waitcnt lgkmcnt(0)
	v_mul_f32_e32 v34, v16, v22
	v_mul_f32_e32 v29, v17, v10
	v_mul_f32_e32 v25, v18, v23
	v_mul_f32_e32 v23, v19, v11
	v_fmac_f32_e32 v77, v39, v39
	ds_read_b128 v[8:11], v76 offset:1536
	ds_read_b128 v[12:15], v76 offset:1552
	v_fmac_f32_e32 v77, v34, v34
	v_fmac_f32_e32 v77, v29, v29
	v_fmac_f32_e32 v77, v25, v25
	v_lshlrev_b32_e32 v16, 16, v4
	v_fmac_f32_e32 v77, v23, v23
	v_and_b32_e32 v4, 0xffff0000, v4
	s_waitcnt lgkmcnt(1)
	v_mul_f32_e32 v50, v8, v16
	v_lshlrev_b32_e32 v17, 16, v5
	v_and_b32_e32 v5, 0xffff0000, v5
	v_lshlrev_b32_e32 v18, 16, v6
	v_and_b32_e32 v6, 0xffff0000, v6
	v_lshlrev_b32_e32 v74, 16, v7
	v_and_b32_e32 v7, 0xffff0000, v7
	v_mul_f32_e32 v26, v9, v4
	v_fmac_f32_e32 v77, v50, v50
	v_mul_f32_e32 v22, v10, v17
	v_mul_f32_e32 v21, v11, v5
	s_waitcnt lgkmcnt(0)
	v_mul_f32_e32 v20, v12, v18
	v_mul_f32_e32 v19, v13, v6
	v_mul_f32_e32 v18, v14, v74
	v_mul_f32_e32 v17, v15, v7
	v_fmac_f32_e32 v77, v26, v26
	v_lshlrev_b32_e32 v4, 16, v0
	v_and_b32_e32 v5, 0xffff0000, v0
	v_lshlrev_b32_e32 v6, 16, v1
	v_and_b32_e32 v7, 0xffff0000, v1
	v_lshlrev_b32_e32 v8, 16, v2
	v_and_b32_e32 v9, 0xffff0000, v2
	v_lshlrev_b32_e32 v74, 16, v3
	v_and_b32_e32 v75, 0xffff0000, v3
	ds_read_b128 v[0:3], v76 offset:1792
	v_fmac_f32_e32 v77, v22, v22
	v_fmac_f32_e32 v77, v21, v21
	v_fmac_f32_e32 v77, v20, v20
	v_fmac_f32_e32 v77, v19, v19
	v_fmac_f32_e32 v77, v18, v18
	s_waitcnt lgkmcnt(0)
	v_pk_mul_f32 v[14:15], v[0:1], v[4:5]
	v_fmac_f32_e32 v77, v17, v17
	v_pk_mul_f32 v[0:1], v[14:15], v[14:15]
	v_pk_mul_f32 v[12:13], v[2:3], v[6:7]
	v_add_f32_e32 v0, v77, v0
	v_add_f32_e32 v4, v0, v1
	v_pk_mul_f32 v[0:1], v[12:13], v[12:13]
	s_lshl_b32 s0, s17, 2
	v_add_f32_e32 v0, v4, v0
	v_add_f32_e32 v4, v0, v1
	ds_read_b128 v[0:3], v76 offset:1808
	s_add_u32 s0, s52, s0
	s_addc_u32 s1, s53, 0
	s_waitcnt lgkmcnt(0)
	v_pk_mul_f32 v[10:11], v[0:1], v[8:9]
	s_nop 0
	v_pk_mul_f32 v[0:1], v[10:11], v[10:11]
	v_pk_mul_f32 v[8:9], v[2:3], v[74:75]
	v_add_f32_e32 v0, v4, v0
	v_add_f32_e32 v4, v0, v1
	v_pk_mul_f32 v[0:1], v[8:9], v[8:9]
	s_nop 0
	v_add_f32_e32 v0, v4, v0
	v_add_f32_e32 v0, v0, v1
	v_cndmask_b32_e32 v1, v185, v188, vcc
	v_lshlrev_b32_e32 v1, 2, v1
	ds_bpermute_b32 v1, v1, v0
	v_cmp_lt_i32_e32 vcc, v189, v187
	s_waitcnt lgkmcnt(0)
	v_add_f32_e32 v0, v0, v1
	v_cndmask_b32_e32 v1, v185, v189, vcc
	v_lshlrev_b32_e32 v1, 2, v1
	ds_bpermute_b32 v1, v1, v0
	v_cmp_lt_i32_e32 vcc, v190, v187
	s_waitcnt lgkmcnt(0)
	v_add_f32_e32 v0, v0, v1
	v_cndmask_b32_e32 v1, v185, v190, vcc
	v_lshlrev_b32_e32 v1, 2, v1
	ds_bpermute_b32 v1, v1, v0
	s_waitcnt lgkmcnt(0)
	v_add_f32_e32 v0, v0, v1
	v_fmamk_f32 v0, v0, 0x3b000000, v182
	v_cmp_gt_f32_e32 vcc, s56, v0
	v_mul_f32_e32 v1, 0x4b800000, v0
	s_nop 0
	v_cndmask_b32_e32 v0, v0, v1, vcc
	v_rsq_f32_e32 v0, v0
	s_nop 0
	v_mul_f32_e32 v1, 0x45800000, v0
	v_cndmask_b32_e32 v16, v0, v1, vcc
	global_load_dwordx4 v[142:145], v32, s[0:1] offset:1792
	v_mul_f32_e32 v73, v73, v16
	v_mul_f32_e32 v69, v69, v16
	v_mul_f32_e32 v68, v68, v16
	v_mul_f32_e32 v67, v67, v16
	v_mul_f32_e32 v72, v72, v16
	v_mul_f32_e32 v71, v71, v16
	v_mul_f32_e32 v70, v70, v16
	v_mul_f32_e32 v51, v51, v16
	v_mul_f32_e32 v60, v60, v16
	v_mul_f32_e32 v56, v56, v16
	v_mul_f32_e32 v20, v20, v16
	v_mul_f32_e32 v22, v22, v16
	v_mul_f32_e32 v21, v21, v16
	v_mul_f32_e32 v10, v10, v16
	v_mul_f32_e32 v12, v12, v16
	v_mul_f32_e32 v13, v13, v16
	s_waitcnt vmcnt(15)
	v_mul_f32_e32 v0, v204, v69
	s_waitcnt vmcnt(14)
	v_mul_f32_e32 v4, v208, v73
	v_mul_f32_e32 v1, v205, v68
	v_mul_f32_e32 v67, v206, v67
	v_mul_f32_e32 v2, v65, v16
	v_mul_f32_e32 v5, v209, v72
	v_mul_f32_e32 v65, v207, v2
	v_cvt_pk_bf16_f32 v2, v4, v5
	v_cvt_pk_bf16_f32 v4, v0, v1
	v_lshl_add_u64 v[0:1], s[8:9], 0, v[108:109]
	v_lshl_add_u64 v[0:1], v[0:1], 0, s[28:29]
	v_lshl_add_u64 v[0:1], v[0:1], 0, v[132:133]
	v_mul_f32_e32 v6, v210, v71
	v_mul_f32_e32 v7, v211, v70
	v_cvt_pk_bf16_f32 v3, v6, v7
	v_cvt_pk_bf16_f32 v5, v67, v65
	global_store_dwordx4 v[0:1], v[2:5], off
	v_mul_f32_e32 v6, v66, v16
	v_mul_f32_e32 v7, v63, v16
	s_waitcnt vmcnt(14)
	v_mul_f32_e32 v51, v51, v212
	v_mul_f32_e32 v2, v45, v16
	v_mul_f32_e32 v45, v2, v213
	v_mul_f32_e32 v2, v40, v16
	v_mul_f32_e32 v40, v2, v214
	v_mul_f32_e32 v2, v35, v16
	v_mul_f32_e32 v5, v2, v215
	s_waitcnt vmcnt(13)
	v_mul_f32_e32 v6, v6, v216
	v_mul_f32_e32 v7, v7, v217
	v_mul_f32_e32 v60, v60, v218
	v_mul_f32_e32 v56, v56, v219
	v_cvt_pk_bf16_f32 v2, v6, v7
	v_cvt_pk_bf16_f32 v3, v60, v56
	v_cvt_pk_bf16_f32 v4, v51, v45
	v_cvt_pk_bf16_f32 v5, v40, v5
	global_store_dwordx4 v[0:1], v[2:5], off offset:128
	v_mul_f32_e32 v45, v46, v16
	v_mul_f32_e32 v6, v64, v16
	v_mul_f32_e32 v7, v61, v16
	v_mul_f32_e32 v35, v57, v16
	v_mul_f32_e32 v40, v52, v16
	s_waitcnt vmcnt(13)
	v_mul_f32_e32 v45, v45, v220
	v_mul_f32_e32 v2, v41, v16
	v_mul_f32_e32 v41, v2, v221
	v_mul_f32_e32 v2, v36, v16
	v_mul_f32_e32 v36, v2, v222
	v_mul_f32_e32 v2, v30, v16
	v_mul_f32_e32 v5, v2, v223
	s_waitcnt vmcnt(12)
	v_mul_f32_e32 v6, v6, v224
	v_mul_f32_e32 v7, v7, v225
	v_mul_f32_e32 v35, v35, v226
	v_mul_f32_e32 v40, v40, v227
	v_cvt_pk_bf16_f32 v2, v6, v7
	v_cvt_pk_bf16_f32 v3, v35, v40
	v_cvt_pk_bf16_f32 v4, v45, v41
	v_cvt_pk_bf16_f32 v5, v36, v5
	global_store_dwordx4 v[0:1], v[2:5], off offset:256
	v_mul_f32_e32 v36, v42, v16
	v_mul_f32_e32 v6, v62, v16
	v_mul_f32_e32 v7, v58, v16
	v_mul_f32_e32 v30, v53, v16
	v_mul_f32_e32 v35, v47, v16
	s_waitcnt vmcnt(12)
	v_mul_f32_e32 v36, v36, v228
	v_mul_f32_e32 v2, v37, v16
	v_mul_f32_e32 v37, v2, v229
	v_mul_f32_e32 v2, v31, v16
	v_mul_f32_e32 v31, v2, v230
	v_mul_f32_e32 v2, v27, v16
	v_mul_f32_e32 v5, v2, v231
	s_waitcnt vmcnt(11)
	v_mul_f32_e32 v6, v6, v232
	v_mul_f32_e32 v7, v7, v233
	v_mul_f32_e32 v30, v30, v234
	v_mul_f32_e32 v35, v35, v235
	v_cvt_pk_bf16_f32 v2, v6, v7
	v_cvt_pk_bf16_f32 v3, v30, v35
	v_cvt_pk_bf16_f32 v4, v36, v37
	v_cvt_pk_bf16_f32 v5, v31, v5
	global_store_dwordx4 v[0:1], v[2:5], off offset:384
	v_mul_f32_e32 v31, v38, v16
	v_mul_f32_e32 v6, v59, v16
	v_mul_f32_e32 v7, v54, v16
	v_mul_f32_e32 v27, v48, v16
	v_mul_f32_e32 v30, v43, v16
	s_waitcnt vmcnt(11)
	v_mul_f32_e32 v31, v31, v236
	v_mul_f32_e32 v2, v33, v16
	v_mul_f32_e32 v33, v2, v237
	v_mul_f32_e32 v2, v28, v16
	v_mul_f32_e32 v28, v2, v238
	v_mul_f32_e32 v2, v24, v16
	v_mul_f32_e32 v5, v2, v239
	s_waitcnt vmcnt(10)
	v_mul_f32_e32 v6, v6, v240
	v_mul_f32_e32 v7, v7, v241
	v_mul_f32_e32 v27, v27, v242
	v_mul_f32_e32 v30, v30, v243
	v_cvt_pk_bf16_f32 v2, v6, v7
	v_cvt_pk_bf16_f32 v3, v27, v30
	v_cvt_pk_bf16_f32 v4, v31, v33
	v_cvt_pk_bf16_f32 v5, v28, v5
	global_store_dwordx4 v[0:1], v[2:5], off offset:512
	v_mul_f32_e32 v28, v34, v16
	v_mul_f32_e32 v6, v55, v16
	v_mul_f32_e32 v7, v49, v16
	v_mul_f32_e32 v24, v44, v16
	v_mul_f32_e32 v27, v39, v16
	s_waitcnt vmcnt(10)
	v_mul_f32_e32 v28, v28, v146
	v_mul_f32_e32 v2, v29, v16
	v_mul_f32_e32 v29, v2, v147
	v_mul_f32_e32 v2, v25, v16
	v_mul_f32_e32 v25, v2, v148
	v_mul_f32_e32 v2, v23, v16
	v_mul_f32_e32 v5, v2, v149
	s_waitcnt vmcnt(9)
	v_mul_f32_e32 v6, v6, v150
	v_mul_f32_e32 v7, v7, v151
	v_mul_f32_e32 v24, v24, v152
	v_mul_f32_e32 v27, v27, v153
	v_cvt_pk_bf16_f32 v2, v6, v7
	v_cvt_pk_bf16_f32 v3, v24, v27
	v_cvt_pk_bf16_f32 v4, v28, v29
	v_cvt_pk_bf16_f32 v5, v25, v5
	global_store_dwordx4 v[0:1], v[2:5], off offset:640
	v_mul_f32_e32 v6, v50, v16
	v_mul_f32_e32 v7, v26, v16
	s_waitcnt vmcnt(9)
	v_mul_f32_e32 v20, v20, v168
	v_mul_f32_e32 v2, v19, v16
	v_mul_f32_e32 v19, v2, v169
	v_mul_f32_e32 v2, v18, v16
	v_mul_f32_e32 v18, v2, v170
	v_mul_f32_e32 v2, v17, v16
	v_mul_f32_e32 v5, v2, v171
	s_waitcnt vmcnt(8)
	v_mul_f32_e32 v6, v6, v172
	v_mul_f32_e32 v7, v7, v173
	v_mul_f32_e32 v22, v22, v174
	v_mul_f32_e32 v21, v21, v175
	v_cvt_pk_bf16_f32 v2, v6, v7
	v_cvt_pk_bf16_f32 v3, v22, v21
	v_cvt_pk_bf16_f32 v4, v20, v19
	v_cvt_pk_bf16_f32 v5, v18, v5
	global_store_dwordx4 v[0:1], v[2:5], off offset:768
	v_mul_f32_e32 v6, v14, v16
	v_mul_f32_e32 v7, v15, v16
	s_mov_b64 s[0:1], 0
	s_waitcnt vmcnt(8)
	v_mul_f32_e32 v10, v10, v176
	v_mul_f32_e32 v2, v11, v16
	v_mul_f32_e32 v11, v2, v177
	v_mul_f32_e32 v2, v8, v16
	v_mul_f32_e32 v8, v2, v178
	v_mul_f32_e32 v2, v9, v16
	v_mul_f32_e32 v5, v2, v179
	s_waitcnt vmcnt(7)
	v_mul_f32_e32 v6, v6, v142
	v_mul_f32_e32 v7, v7, v143
	v_mul_f32_e32 v12, v12, v144
	v_mul_f32_e32 v13, v13, v145
	v_cvt_pk_bf16_f32 v2, v6, v7
	v_cvt_pk_bf16_f32 v3, v12, v13
	v_cvt_pk_bf16_f32 v4, v10, v11
	v_cvt_pk_bf16_f32 v5, v8, v5
	global_store_dwordx4 v[0:1], v[2:5], off offset:896
	s_barrier
